# v47
# baseline (speedup 1.0000x reference)
.LBB0_742:
	v_add_u32_e32 v191, s36, v169
	v_add3_u32 v196, v191, v168, v208
	ds_read_b128 v[64:67], v196
	ds_read_b128 v[192:195], v196 offset:4608
	v_mov_b64_e32 v[110:111], s[30:31]
	v_mov_b64_e32 v[108:109], s[28:29]
	v_mov_b64_e32 v[106:107], s[26:27]
	v_mov_b64_e32 v[104:105], s[24:25]
	v_mov_b64_e32 v[102:103], s[22:23]
	v_mov_b64_e32 v[100:101], s[20:21]
	v_mov_b64_e32 v[98:99], s[18:19]
	v_mov_b64_e32 v[96:97], s[16:17]
	v_cvt_f32_i32_e32 v197, v190
	s_mov_b64 s[50:51], 0x40000
	s_waitcnt lgkmcnt(1)
	v_mfma_f32_32x32x16_bf16 v[80:95], v[64:67], v[112:115], v[96:111]
	s_waitcnt lgkmcnt(0)
	v_mfma_f32_32x32x16_bf16 v[64:79], v[192:195], v[112:115], v[96:111]
	s_add_i32 s38, s38, 1
	v_add_f32_e32 v198, -2.0, v197
	v_add_f32_e32 v199, 0xc1300000, v197
	v_add_f32_e32 v200, 0xc1800000, v197
	v_add_f32_e32 v201, 0xc1880000, v197
	v_lshl_add_u64 v[162:163], v[162:163], 0, s[50:51]
	v_lshl_add_u64 v[164:165], v[164:165], 0, s[40:41]
	ds_read_b128 v[96:99], v196 offset:32
	ds_read_b128 v[100:103], v196 offset:64
	s_and_b64 vcc, exec, s[56:57]
	s_waitcnt lgkmcnt(1)
	v_mfma_f32_32x32x16_bf16 v[80:95], v[96:99], v[116:119], v[80:95]
	ds_read_b128 v[96:99], v196 offset:4640
	ds_read_b128 v[104:107], v196 offset:4672
	ds_read_b128 v[108:111], v196 offset:96
	ds_read_b128 v[192:195], v196 offset:4704
	v_add_f32_e32 v196, -1.0, v197
	s_waitcnt lgkmcnt(4)
	v_mfma_f32_32x32x16_bf16 v[80:95], v[100:103], v[120:123], v[80:95]
	v_add_f32_e32 v100, 0xc0400000, v197
	v_add_f32_e32 v101, 0xc1000000, v197
	v_add_f32_e32 v102, 0xc1100000, v197
	v_add_f32_e32 v103, 0xc1200000, v197
	s_waitcnt lgkmcnt(1)
	v_mfma_f32_32x32x16_bf16 v[80:95], v[108:111], v[124:127], v[80:95]
	v_mfma_f32_32x32x16_bf16 v[64:79], v[96:99], v[116:119], v[64:79]
	s_nop 10
	v_fma_f32 v80, -v144, |v197|, v80
	v_exp_f32_e32 v108, v80
	v_add_f32_e32 v80, 0xc1900000, v197
	v_fma_f32 v80, -v144, |v80|, v90
	v_exp_f32_e32 v203, v80
	v_add_f32_e32 v80, 0xc1980000, v197
	v_lshl_add_u32 v96, v170, 1, v191
	v_mfma_f32_32x32x16_bf16 v[64:79], v[104:107], v[120:123], v[64:79]
	v_fma_f32 v81, -v144, |v196|, v81
	v_fma_f32 v82, -v144, |v198|, v82
	v_fma_f32 v83, -v144, |v100|, v83
	v_fma_f32 v84, -v144, |v101|, v84
	v_fma_f32 v85, -v144, |v102|, v85
	v_fma_f32 v86, -v144, |v103|, v86
	v_fma_f32 v87, -v144, |v199|, v87
	v_fma_f32 v80, -v144, |v80|, v91
	v_add_u32_e32 v191, 0x4800, v96
	v_fma_f32 v88, -v144, |v200|, v88
	v_exp_f32_e32 v109, v81
	v_exp_f32_e32 v110, v82
	v_exp_f32_e32 v111, v83
	v_exp_f32_e32 v196, v84
	v_exp_f32_e32 v198, v85
	v_exp_f32_e32 v199, v86
	v_exp_f32_e32 v200, v87
	v_exp_f32_e32 v204, v80
	v_cvt_pk_bf16_f32 v80, v108, v109
	v_cvt_pk_bf16_f32 v81, v110, v111
	v_cvt_pk_bf16_f32 v82, v196, v198
	v_cvt_pk_bf16_f32 v83, v199, v200
	ds_read2_b64 v[84:87], v191 offset1:2
	v_fma_f32 v89, -v144, |v201|, v89
	v_exp_f32_e32 v201, v88
	v_add_f32_e32 v88, 0xc1c00000, v197
	v_fma_f32 v88, -v144, |v88|, v92
	s_waitcnt lgkmcnt(1)
	v_mfma_f32_32x32x16_bf16 v[64:79], v[192:195], v[124:127], v[64:79]
	v_exp_f32_e32 v192, v88
	v_add_f32_e32 v88, 0xc1c80000, v197
	v_fma_f32 v88, -v144, |v88|, v93
	v_add_u32_e32 v194, 0x5800, v96
	v_exp_f32_e32 v202, v89
	v_exp_f32_e32 v193, v88
	ds_read2_b64 v[88:91], v194 offset0:64 offset1:66
	s_waitcnt lgkmcnt(1)
	v_mfma_f32_32x32x16_bf16 v[48:63], v[84:87], v[80:83], v[48:63]
	v_add_f32_e32 v84, 0xc1d00000, v197
	v_fma_f32 v84, -v144, |v84|, v94
	v_exp_f32_e32 v195, v84
	v_add_f32_e32 v84, 0xc1d80000, v197
	v_add_u32_e32 v197, 0x6800, v96
	v_fma_f32 v92, -v144, |v84|, v95
	ds_read2_b64 v[84:87], v197 offset0:128 offset1:130
	v_add_u32_e32 v206, 0x7800, v96
	s_waitcnt lgkmcnt(1)
	v_mfma_f32_32x32x16_bf16 v[32:47], v[88:91], v[80:83], v[32:47]
	ds_read2_b64 v[88:91], v206 offset0:192 offset1:194
	v_subrev_u32_e32 v96, 32, v190
	v_cvt_f32_i32_e32 v207, v96
	v_exp_f32_e32 v205, v92
	v_cvt_pk_bf16_f32 v92, v201, v202
	v_cvt_pk_bf16_f32 v93, v203, v204
	v_cvt_pk_bf16_f32 v94, v192, v193
	v_cvt_pk_bf16_f32 v95, v195, v205
	s_waitcnt lgkmcnt(1)
	v_mfma_f32_32x32x16_bf16 v[16:31], v[84:87], v[80:83], v[16:31]
	ds_read2_b64 v[84:87], v191 offset0:4 offset1:6
	v_fma_f32 v64, -v144, |v207|, v64
	ds_read2_b64 v[96:99], v194 offset0:68 offset1:70
	ds_read2_b64 v[100:103], v197 offset0:132 offset1:134
	ds_read2_b64 v[104:107], v206 offset0:196 offset1:198
	v_subrev_u32_e32 v190, 64, v190
	s_waitcnt lgkmcnt(4)
	v_mfma_f32_32x32x16_bf16 v[0:15], v[88:91], v[80:83], v[0:15]
	v_exp_f32_e32 v88, v64
	v_add_f32_e32 v64, -1.0, v207
	v_fma_f32 v64, -v144, |v64|, v65
	v_exp_f32_e32 v89, v64
	v_add_f32_e32 v64, -2.0, v207
	v_fma_f32 v64, -v144, |v64|, v66
	v_exp_f32_e32 v90, v64
	v_add_f32_e32 v64, 0xc0400000, v207
	v_fma_f32 v64, -v144, |v64|, v67
	s_waitcnt lgkmcnt(3)
	v_mfma_f32_32x32x16_bf16 v[48:63], v[84:87], v[92:95], v[48:63]
	v_exp_f32_e32 v84, v64
	v_add_f32_e32 v64, 0xc1000000, v207
	v_fma_f32 v64, -v144, |v64|, v68
	v_exp_f32_e32 v85, v64
	v_add_f32_e32 v64, 0xc1100000, v207
	v_fma_f32 v64, -v144, |v64|, v69
	v_exp_f32_e32 v86, v64
	v_add_f32_e32 v64, 0xc1200000, v207
	v_fma_f32 v64, -v144, |v64|, v70
	v_exp_f32_e32 v87, v64
	v_add_f32_e32 v64, 0xc1300000, v207
	v_fma_f32 v64, -v144, |v64|, v71
	v_exp_f32_e32 v91, v64
	v_cvt_pk_bf16_f32 v64, v88, v89
	v_cvt_pk_bf16_f32 v65, v90, v84
	v_cvt_pk_bf16_f32 v66, v85, v86
	v_cvt_pk_bf16_f32 v67, v87, v91
	ds_read2_b64 v[68:71], v191 offset0:8 offset1:10
	v_add_f32_e32 v80, 0xc1800000, v207
	v_fma_f32 v72, -v144, |v80|, v72
	s_waitcnt lgkmcnt(3)
	v_mfma_f32_32x32x16_bf16 v[32:47], v[96:99], v[92:95], v[32:47]
	ds_read2_b64 v[80:83], v194 offset0:72 offset1:74
	s_waitcnt lgkmcnt(3)
	v_mfma_f32_32x32x16_bf16 v[16:31], v[100:103], v[92:95], v[16:31]
	s_waitcnt lgkmcnt(2)
	v_mfma_f32_32x32x16_bf16 v[0:15], v[104:107], v[92:95], v[0:15]
	v_exp_f32_e32 v92, v72
	v_add_f32_e32 v72, 0xc1880000, v207
	v_fma_f32 v72, -v144, |v72|, v73
	v_exp_f32_e32 v93, v72
	v_add_f32_e32 v72, 0xc1900000, v207
	s_waitcnt lgkmcnt(1)
	v_mfma_f32_32x32x16_bf16 v[48:63], v[68:71], v[64:67], v[48:63]
	v_fma_f32 v68, -v144, |v72|, v74
	v_exp_f32_e32 v94, v68
	v_add_f32_e32 v68, 0xc1980000, v207
	v_fma_f32 v68, -v144, |v68|, v75
	v_add_f32_e32 v72, 0xc1c00000, v207
	v_exp_f32_e32 v95, v68
	ds_read2_b64 v[68:71], v197 offset0:136 offset1:138
	v_fma_f32 v72, -v144, |v72|, v76
	v_exp_f32_e32 v76, v72
	v_add_f32_e32 v72, 0xc1c80000, v207
	v_fma_f32 v72, -v144, |v72|, v77
	v_exp_f32_e32 v77, v72
	ds_read2_b64 v[72:75], v206 offset0:200 offset1:202
	s_waitcnt lgkmcnt(2)
	v_mfma_f32_32x32x16_bf16 v[32:47], v[80:83], v[64:67], v[32:47]
	v_add_f32_e32 v80, 0xc1d00000, v207
	s_waitcnt lgkmcnt(1)
	v_mfma_f32_32x32x16_bf16 v[16:31], v[68:71], v[64:67], v[16:31]
	v_fma_f32 v68, -v144, |v80|, v78
	v_exp_f32_e32 v78, v68
	v_add_f32_e32 v68, 0xc1d80000, v207
	v_fma_f32 v68, -v144, |v68|, v79
	v_exp_f32_e32 v79, v68
	v_cvt_pk_bf16_f32 v68, v92, v93
	v_cvt_pk_bf16_f32 v69, v94, v95
	s_waitcnt lgkmcnt(0)
	v_mfma_f32_32x32x16_bf16 v[0:15], v[72:75], v[64:67], v[0:15]
	v_cvt_pk_bf16_f32 v70, v76, v77
	v_cvt_pk_bf16_f32 v71, v78, v79
	ds_read2_b64 v[64:67], v191 offset0:12 offset1:14
	v_add_f32_e32 v72, v161, v108
	v_add_f32_e32 v80, v109, v72
	ds_read2_b64 v[72:75], v194 offset0:76 offset1:78
	s_waitcnt lgkmcnt(1)
	v_mfma_f32_32x32x16_bf16 v[48:63], v[64:67], v[68:71], v[48:63]
	v_add_f32_e32 v64, v110, v80
	v_add_f32_e32 v64, v111, v64
	v_add_f32_e32 v64, v196, v64
	v_add_f32_e32 v64, v198, v64
	v_add_f32_e32 v64, v199, v64
	v_add_f32_e32 v80, v200, v64
	ds_read2_b64 v[64:67], v197 offset0:140 offset1:142
	s_waitcnt lgkmcnt(1)
	v_mfma_f32_32x32x16_bf16 v[32:47], v[72:75], v[68:71], v[32:47]
	v_add_f32_e32 v72, v201, v80
	v_add_f32_e32 v72, v202, v72
	v_add_f32_e32 v72, v203, v72
	v_add_f32_e32 v72, v204, v72
	v_add_f32_e32 v72, v192, v72
	v_add_f32_e32 v80, v193, v72
	ds_read2_b64 v[72:75], v206 offset0:204 offset1:206
	s_waitcnt lgkmcnt(1)
	v_mfma_f32_32x32x16_bf16 v[16:31], v[64:67], v[68:71], v[16:31]
	v_add_f32_e32 v64, v195, v80
	v_add_f32_e32 v64, v205, v64
	v_add_f32_e32 v64, v88, v64
	v_add_f32_e32 v64, v89, v64
	v_add_f32_e32 v64, v90, v64
	v_add_f32_e32 v64, v84, v64
	v_add_f32_e32 v64, v85, v64
	v_add_f32_e32 v64, v86, v64
	v_add_f32_e32 v64, v87, v64
	v_add_f32_e32 v64, v91, v64
	s_waitcnt lgkmcnt(0)
	v_mfma_f32_32x32x16_bf16 v[0:15], v[72:75], v[68:71], v[0:15]
	v_add_f32_e32 v64, v92, v64
	v_add_f32_e32 v64, v93, v64
	v_add_f32_e32 v64, v94, v64
	v_add_f32_e32 v64, v95, v64
	v_add_f32_e32 v64, v76, v64
	v_add_f32_e32 v64, v77, v64
	v_add_f32_e32 v64, v78, v64
	v_add_f32_e32 v161, v79, v64
	s_cbranch_vccnz .LBB0_745
